# GEMM phase start: the first tile's rstd partial-sum loads are issued together and waited once (was two serialized round trips)
# baseline (speedup 1.0000x reference)
; DI float row_rstd(const float* P, int np, float inv_dim, int row) {
;   float s = P[row];
;   if (np > 1) s += P[T + row];
;   if (np > 2) s += P[2 * T + row] + P[3 * T + row];
;   return rsqrtf(s * inv_dim + EPS);
; }
; DI void gemm_phase(LAS unsigned char* lds, const GemmDesc& d, float* __restrict__ X) {
;     ...
;     if (ui == 0 && d.epi != EPI_RESID) { if (ktid < 256) rsl[ktid] = row_rstd(d.P, d.np, d.inv_dim, pm * 256 + ktid); }
.LBB0_339:
	s_lshl_b32 s14, s20, 10
	s_and_b32 s14, s14, 0x400
	s_add_i32 s38, s14, 0
	s_add_i32 s38, s38, 0x20000
	s_cmp_eq_u32 s20, 0
	s_cselect_b64 s[20:21], -1, 0
	v_cndmask_b32_e64 v0, 0, 1, s[40:41]
	s_and_b64 s[20:21], s[20:21], s[76:77]
	v_cmp_ne_u32_e64 s[46:47], 1, v0
	s_and_saveexec_b64 s[78:79], s[20:21]
	s_cbranch_execz .LBB0_345
	s_lshl_b32 s20, s97, 8
	s_ashr_i32 s21, s20, 31
	v_lshl_add_u64 v[2:3], s[20:21], 2, v[156:157]
	global_load_dword v0, v[2:3], off
	v_mov_b32_e32 v6, 0
	v_mov_b32_e32 v7, 0
	v_mov_b32_e32 v8, 0
	s_and_b64 vcc, exec, s[46:47]
	s_cbranch_vccnz .Lrs_a
	v_add_co_u32_e32 v4, vcc, 0x20000, v2
	s_nop 1
	v_addc_co_u32_e32 v5, vcc, 0, v3, vcc
	global_load_dword v6, v[4:5], off
.Lrs_a:
	s_andn2_b64 vcc, exec, s[48:49]
	s_cbranch_vccnz .Lrs_b
	v_add_co_u32_e32 v10, vcc, 0x40000, v2
	s_nop 1
	v_addc_co_u32_e32 v11, vcc, 0, v3, vcc
	v_add_co_u32_e32 v12, vcc, 0x60000, v2
	s_nop 1
	v_addc_co_u32_e32 v13, vcc, 0, v3, vcc
	global_load_dword v7, v[10:11], off
	global_load_dword v8, v[12:13], off
.Lrs_b:
	s_waitcnt vmcnt(0)
	v_add_f32_e32 v0, v0, v6
	v_add_f32_e32 v2, v7, v8
	v_add_f32_e32 v0, v0, v2
